# v89 + one-time grid-barrier census: 16 per-XCD counter loads issued together instead of 16 serialized round trips
# baseline (speedup 1.0000x reference)
.LBB0_858:
	s_mov_b64 s[4:5], -1
	v_readlane_b32 s2, v252, 44
	v_readlane_b32 s3, v252, 45
	s_nop 4
	global_load_dword v0, v161, s[2:3] sc1
	v_readlane_b32 s2, v252, 46
	v_readlane_b32 s3, v252, 47
	s_nop 4
	global_load_dword v1, v161, s[2:3] sc1
	v_readlane_b32 s2, v252, 48
	v_readlane_b32 s3, v252, 49
	s_nop 4
	global_load_dword v2, v161, s[2:3] sc1
	v_readlane_b32 s2, v252, 50
	v_readlane_b32 s3, v252, 51
	s_nop 4
	global_load_dword v3, v161, s[2:3] sc1
	v_readlane_b32 s2, v252, 52
	v_readlane_b32 s3, v252, 53
	s_nop 4
	global_load_dword v4, v161, s[2:3] sc1
	v_readlane_b32 s2, v252, 54
	v_readlane_b32 s3, v252, 55
	s_nop 4
	global_load_dword v5, v161, s[2:3] sc1
	v_readlane_b32 s2, v252, 56
	v_readlane_b32 s3, v252, 57
	s_nop 4
	global_load_dword v6, v161, s[2:3] sc1
	v_readlane_b32 s2, v252, 58
	v_readlane_b32 s3, v252, 59
	s_nop 4
	global_load_dword v7, v161, s[2:3] sc1
	v_readlane_b32 s2, v252, 60
	v_readlane_b32 s3, v252, 61
	s_nop 4
	global_load_dword v8, v161, s[2:3] sc1
	v_readlane_b32 s2, v252, 62
	v_readlane_b32 s3, v252, 63
	s_nop 4
	global_load_dword v9, v161, s[2:3] sc1
	v_readlane_b32 s2, v253, 0
	v_readlane_b32 s3, v253, 1
	s_nop 4
	global_load_dword v10, v161, s[2:3] sc1
	v_readlane_b32 s2, v253, 2
	v_readlane_b32 s3, v253, 3
	s_nop 4
	global_load_dword v11, v161, s[2:3] sc1
	v_readlane_b32 s2, v253, 4
	v_readlane_b32 s3, v253, 5
	s_nop 4
	global_load_dword v12, v161, s[2:3] sc1
	v_readlane_b32 s2, v253, 6
	v_readlane_b32 s3, v253, 7
	s_nop 4
	global_load_dword v13, v161, s[2:3] sc1
	v_readlane_b32 s2, v253, 8
	v_readlane_b32 s3, v253, 9
	s_nop 4
	global_load_dword v14, v161, s[2:3] sc1
	v_readlane_b32 s2, v253, 10
	v_readlane_b32 s3, v253, 11
	s_nop 4
	global_load_dword v15, v161, s[2:3] sc1
	s_nop 4
	s_mov_b64 s[2:3], -1
	s_waitcnt vmcnt(0)
	v_add_u32_e32 v16, v1, v0
	v_add_u32_e32 v16, v16, v2
	v_add_u32_e32 v16, v16, v3
	v_add_u32_e32 v16, v16, v4
	v_add_u32_e32 v16, v16, v5
	v_add_u32_e32 v16, v16, v6
	v_add_u32_e32 v16, v16, v7
	v_add_u32_e32 v16, v16, v8
	v_add_u32_e32 v16, v16, v9
	v_add_u32_e32 v16, v16, v10
	v_add_u32_e32 v16, v16, v11
	v_add_u32_e32 v16, v16, v12
	v_add_u32_e32 v16, v16, v13
	v_add_u32_e32 v16, v16, v14
	v_add_u32_e32 v16, v16, v15
	v_cmp_eq_u32_e32 vcc, s8, v16
	s_cbranch_vccnz .LBB0_857
	s_and_b32 s2, s9, 0xff
	s_cmp_eq_u32 s2, 0
	s_mov_b64 s[2:3], -1
	s_mov_b64 s[6:7], -1
	s_sleep 1
	s_cbranch_scc0 .LBB0_862
	v_readlane_b32 s2, v252, 42
	v_readlane_b32 s3, v252, 43
	s_nop 4
	global_load_dword v16, v161, s[2:3] sc1
	s_waitcnt vmcnt(0)
	v_cmp_eq_u32_e32 vcc, 0, v16
	s_cbranch_vccnz .LBB0_864
	s_mov_b64 s[6:7], 0
	s_mov_b64 s[2:3], -1
